# grid barrier spin loops poll without s_sleep (s_sleep 0); barrier protocol and fences unchanged from v183
# baseline (speedup 1.0000x reference)
.LBB0_1504:
	s_and_b32 s21, s20, 0xff
	s_mov_b64 s[22:23], -1
	s_cmp_lg_u32 s21, 0
	s_mov_b64 s[30:31], -1
	s_sleep 0
	s_cbranch_scc0 .LBB0_1507
	s_and_b64 vcc, exec, s[30:31]
	s_cbranch_vccz .LBB0_1503
